# attn2 first unrolled half: online-softmax rescale in place (removes 32-48 v_mov_b64 phi copies per step on rescale / no-rescale paths)
# speedup vs baseline: 1.0056x; 1.0056x over previous
;     ...
;             if (__ballot(shift != 0.f) != 0) {
;                 if (__ballot(up) != 0) {
;                     const float alpha = __builtin_amdgcn_exp2f(m - mn);
;                     l *= alpha;
; #pragma unroll
;                     for (int db = 0; db < DVB; ++db)
; #pragma unroll
;                         for (int i = 0; i < 16; ++i) o[db][i] *= alpha;
;                     m = mn;
;                 }
; #pragma unroll
;                 for (int blk = 0; blk < 2; ++blk)
; #pragma unroll
;                     for (int i = 0; i < 16; ++i) s[blk][i] -= shift;
.Lil1_cont:
	v_cndmask_b32_e64 v34, 0, 1, s[4:5]
	v_cmp_ne_u32_e32 vcc, 0, v34
	s_cbranch_vccz .Lrs1_nosc
	v_sub_f32_e32 v34, v183, v189
	v_exp_f32_e32 v34, v34
	s_nop 0
	v_mul_f32_e32 v173, v173, v34
	v_pk_mul_f32 v[112:113], v[112:113], v[34:35] op_sel_hi:[1,0]
	v_pk_mul_f32 v[110:111], v[110:111], v[34:35] op_sel_hi:[1,0]
	v_pk_mul_f32 v[108:109], v[108:109], v[34:35] op_sel_hi:[1,0]
	v_pk_mul_f32 v[106:107], v[106:107], v[34:35] op_sel_hi:[1,0]
	v_pk_mul_f32 v[104:105], v[104:105], v[34:35] op_sel_hi:[1,0]
	v_pk_mul_f32 v[102:103], v[102:103], v[34:35] op_sel_hi:[1,0]
	v_pk_mul_f32 v[100:101], v[100:101], v[34:35] op_sel_hi:[1,0]
	v_pk_mul_f32 v[98:99], v[98:99], v[34:35] op_sel_hi:[1,0]
	v_pk_mul_f32 v[96:97], v[96:97], v[34:35] op_sel_hi:[1,0]
	v_pk_mul_f32 v[94:95], v[94:95], v[34:35] op_sel_hi:[1,0]
	v_pk_mul_f32 v[92:93], v[92:93], v[34:35] op_sel_hi:[1,0]
	v_pk_mul_f32 v[90:91], v[90:91], v[34:35] op_sel_hi:[1,0]
	v_pk_mul_f32 v[88:89], v[88:89], v[34:35] op_sel_hi:[1,0]
	v_pk_mul_f32 v[86:87], v[86:87], v[34:35] op_sel_hi:[1,0]
	v_pk_mul_f32 v[84:85], v[84:85], v[34:35] op_sel_hi:[1,0]
	v_pk_mul_f32 v[82:83], v[82:83], v[34:35] op_sel_hi:[1,0]
	s_branch .Lrs1_sub
.Lrs1_nosc:
	v_mov_b32_e32 v189, v183
.Lrs1_sub:
	v_sub_f32_e32 v18, v18, v176
	v_sub_f32_e32 v19, v19, v176
	v_sub_f32_e32 v20, v20, v176
	v_sub_f32_e32 v21, v21, v176
	v_sub_f32_e32 v22, v22, v176
	v_sub_f32_e32 v23, v23, v176
	v_sub_f32_e32 v24, v24, v176
	v_sub_f32_e32 v25, v25, v176
	v_sub_f32_e32 v26, v26, v176
	v_sub_f32_e32 v27, v27, v176
	v_sub_f32_e32 v28, v28, v176
	v_sub_f32_e32 v29, v29, v176
	v_sub_f32_e32 v30, v30, v176
	v_sub_f32_e32 v31, v31, v176
	v_sub_f32_e32 v32, v32, v176
	v_sub_f32_e32 v33, v33, v176
	v_sub_f32_e32 v2, v2, v176
	v_sub_f32_e32 v1, v1, v176
	v_sub_f32_e32 v4, v4, v176
	v_sub_f32_e32 v17, v17, v176
	v_sub_f32_e32 v16, v16, v176
	v_sub_f32_e32 v5, v5, v176
	v_sub_f32_e32 v6, v6, v176
	v_sub_f32_e32 v7, v7, v176
	v_sub_f32_e32 v8, v8, v176
	v_sub_f32_e32 v9, v9, v176
	v_sub_f32_e32 v10, v10, v176
	v_sub_f32_e32 v11, v11, v176
	v_sub_f32_e32 v12, v12, v176
	v_sub_f32_e32 v13, v13, v176
	v_sub_f32_e32 v14, v14, v176
	v_sub_f32_e32 v15, v15, v176
	v_mov_b32_e32 v183, v189

;     ...
;         auto stepf = [&](f32x16 (&s_cur)[2], const float mi_cur, f32x16 (&s_nxt)[2], float& mi_nxt, u32x4 (&rg_ld)[NJ], float& ck_ld, const u32x4 (&rg_st)[NJ], const float ck_st, int kk) {
;             const int kt = j0 + kk;
;             if (DEEP) { if (kk + 3 < ntl) gload(rg_ld, ck_ld, kt + 3); } else { if (kk + 2 < ntl) gload(rg_ld, ck_ld, kt + 2); }
;             if (MODE == 2 && kk + 2 < ntl) wnext2 = mrow[kt + 2];
;             if (kk + 1 < ntl && (kt + 1) * 64 <= qw0 + 31) qk(s_nxt, mi_nxt, (kk + 1) % 3);
;             if (kt * 64 <= qw0 + 31) softmax_pv(s_cur, mi_cur, kt, kk % 3);
;             if (MODE == 2) { wcur = wnext; wnext = wnext2; }
;             if (kk + 2 < ntl) lstore(rg_st, ck_st, (kk + 2) % 3);
;             __syncthreads();
.LBB0_3631:
	s_waitcnt vmcnt(0)
	v_mov_b64_e32 v[114:115], v[190:191]
	v_mov_b64_e32 v[116:117], v[192:193]
	s_branch .LBB0_3639
.LBB0_3633:
	v_mov_b32_e32 v50, v183
